# P0 adaLN GEMV: the four serialized c loads + silu issued as four parallel loads
# speedup vs baseline: 1.0021x; 1.0021x over previous
; __global__ void __launch_bounds__(NTHR, 2) hybrid_fwd(Args a) {
;     ...
;             for (int i = tid; i < BATCH * D; i += NTHR) { const float v = a.c[i]; sc_l[i] = v / (1.0f + __expf(-v)); }
;             __syncthreads();
;             const int l = task / 96, n0 = (task % 96) * 32, kc = wave * 2 + (lane >> 5), n = n0 + (lane & 31);
;             const float* W = a.ada_w + (size_t)l * D * 3072 + (size_t)(kc * 64) * 3072 + n;
;             float a0 = 0.f, a1 = 0.f;
; #pragma unroll
;             for (int k = 0; k < 64; ++k) { const float wv = W[(size_t)k * 3072]; a0 += sc_l[kc * 64 + k] * wv; a1 += sc_l[D + kc * 64 + k] * wv; }
;             red[(kc * 2 + 0) * 32 + (lane & 31)] = a0; red[(kc * 2 + 1) * 32 + (lane & 31)] = a1;
.LBB0_12:
	global_load_dword v6, v[16:17], off
	global_load_dword v27, v[16:17], off offset:2048
	v_lshl_add_u64 v[2:3], v[16:17], 0, s[4:5]
	v_lshl_add_u64 v[2:3], v[2:3], 0, s[4:5]
	global_load_dword v28, v[2:3], off
	global_load_dword v29, v[2:3], off offset:2048
	s_waitcnt vmcnt(3)
	v_mul_f32_e32 v7, 0xbfb8aa3b, v6
	v_exp_f32_e32 v7, v7
	s_nop 0
	v_add_f32_e32 v7, 1.0, v7
	v_div_scale_f32 v8, s[58:59], v7, v7, v6
	v_rcp_f32_e32 v9, v8
	v_div_scale_f32 v10, vcc, v6, v7, v6
	v_fma_f32 v11, -v8, v9, 1.0
	v_fmac_f32_e32 v9, v11, v9
	v_mul_f32_e32 v11, v10, v9
	v_fma_f32 v12, -v8, v11, v10
	v_fmac_f32_e32 v11, v12, v9
	v_fma_f32 v8, -v8, v11, v10
	v_div_fmas_f32 v8, v8, v9, v11
	v_div_fixup_f32 v6, v8, v7, v6
	ds_write_b32 v24, v6
	s_waitcnt vmcnt(2)
	v_mul_f32_e32 v7, 0xbfb8aa3b, v27
	v_exp_f32_e32 v7, v7
	s_nop 0
	v_add_f32_e32 v7, 1.0, v7
	v_div_scale_f32 v8, s[58:59], v7, v7, v27
	v_rcp_f32_e32 v9, v8
	v_div_scale_f32 v10, vcc, v27, v7, v27
	v_fma_f32 v11, -v8, v9, 1.0
	v_fmac_f32_e32 v9, v11, v9
	v_mul_f32_e32 v11, v10, v9
	v_fma_f32 v12, -v8, v11, v10
	v_fmac_f32_e32 v11, v12, v9
	v_fma_f32 v8, -v8, v11, v10
	v_div_fmas_f32 v8, v8, v9, v11
	v_div_fixup_f32 v27, v8, v7, v27
	ds_write_b32 v24, v27 offset:2048
	s_waitcnt vmcnt(1)
	v_mul_f32_e32 v7, 0xbfb8aa3b, v28
	v_exp_f32_e32 v7, v7
	s_nop 0
	v_add_f32_e32 v7, 1.0, v7
	v_div_scale_f32 v8, s[58:59], v7, v7, v28
	v_rcp_f32_e32 v9, v8
	v_div_scale_f32 v10, vcc, v28, v7, v28
	v_fma_f32 v11, -v8, v9, 1.0
	v_fmac_f32_e32 v9, v11, v9
	v_mul_f32_e32 v11, v10, v9
	v_fma_f32 v12, -v8, v11, v10
	v_fmac_f32_e32 v11, v12, v9
	v_fma_f32 v8, -v8, v11, v10
	v_div_fmas_f32 v8, v8, v9, v11
	v_div_fixup_f32 v28, v8, v7, v28
	ds_write_b32 v24, v28 offset:4096
	s_waitcnt vmcnt(0)
	v_mul_f32_e32 v7, 0xbfb8aa3b, v29
	v_exp_f32_e32 v7, v7
	s_nop 0
	v_add_f32_e32 v7, 1.0, v7
	v_div_scale_f32 v8, s[58:59], v7, v7, v29
	v_rcp_f32_e32 v9, v8
	v_div_scale_f32 v10, vcc, v29, v7, v29
	v_fma_f32 v11, -v8, v9, 1.0
	v_fmac_f32_e32 v9, v11, v9
	v_mul_f32_e32 v11, v10, v9
	v_fma_f32 v12, -v8, v11, v10
	v_fmac_f32_e32 v11, v12, v9
	v_fma_f32 v8, -v8, v11, v10
	v_div_fmas_f32 v8, v8, v9, v11
	v_div_fixup_f32 v29, v8, v7, v29
	ds_write_b32 v24, v29 offset:6144
	s_mul_hi_i32 s6, s98, 0x2aaaaaab
	s_lshr_b32 s7, s6, 31
	s_ashr_i32 s99, s6, 4
	s_add_i32 s99, s99, s7
	s_mul_i32 s6, s99, 0x60
	s_sub_i32 s6, s98, s6
	s_lshl_b32 s58, s6, 5
	v_or_b32_e32 v2, s58, v1
	v_mad_i64_i32 v[4:5], s[6:7], s99, v25, v[14:15]
	v_ashrrev_i32_e32 v3, 31, v2
	v_lshl_add_u64 v[18:19], v[2:3], 2, v[4:5]
	v_add_co_u32_e32 v10, vcc, s8, v18
	s_movk_i32 s6, 0x6000
	s_nop 0
	v_addc_co_u32_e32 v11, vcc, 0, v19, vcc
	v_add_co_u32_e32 v12, vcc, s6, v18
	s_mov_b32 s6, 0x9000
	s_nop 0
	v_addc_co_u32_e32 v13, vcc, 0, v19, vcc
	v_add_co_u32_e32 v28, vcc, s6, v18
	s_mov_b32 s6, 0xc000
	s_nop 0
	v_addc_co_u32_e32 v29, vcc, 0, v19, vcc
	v_add_co_u32_e32 v30, vcc, s6, v18
	s_mov_b32 s6, 0xf000
	s_nop 0
	v_addc_co_u32_e32 v31, vcc, 0, v19, vcc
	v_add_co_u32_e32 v32, vcc, s6, v18
	s_mov_b32 s6, 0x12000
	s_nop 0
	v_addc_co_u32_e32 v33, vcc, 0, v19, vcc
	v_add_co_u32_e32 v34, vcc, s6, v18
	s_mov_b32 s6, 0x15000
	s_nop 0
	v_addc_co_u32_e32 v35, vcc, 0, v19, vcc
	v_add_co_u32_e32 v36, vcc, s6, v18
	s_mov_b32 s6, 0x18000
	s_nop 0
	v_addc_co_u32_e32 v37, vcc, 0, v19, vcc
	s_waitcnt lgkmcnt(0)
	s_barrier
	ds_read_b128 v[6:9], v20
	ds_read_b128 v[2:5], v20 offset:16
	global_load_dword v27, v[18:19], off
	global_load_dword v40, v[10:11], off
	global_load_dword v41, v[12:13], off
	global_load_dword v42, v[28:29], off
	global_load_dword v43, v[30:31], off
	global_load_dword v44, v[32:33], off
	global_load_dword v45, v[34:35], off
	global_load_dword v46, v[36:37], off
	v_add_co_u32_e32 v10, vcc, s6, v18
	s_mov_b32 s6, 0x1b000
	s_nop 0
	v_addc_co_u32_e32 v11, vcc, 0, v19, vcc
	v_add_co_u32_e32 v12, vcc, s6, v18
	s_mov_b32 s6, 0x1e000
	s_nop 0
	v_addc_co_u32_e32 v13, vcc, 0, v19, vcc
	v_add_co_u32_e32 v28, vcc, s6, v18
	s_mov_b32 s6, 0x21000
	s_nop 0
	v_addc_co_u32_e32 v29, vcc, 0, v19, vcc
	v_add_co_u32_e32 v30, vcc, s6, v18
	s_mov_b32 s6, 0x24000
	s_nop 0
	v_addc_co_u32_e32 v31, vcc, 0, v19, vcc
	v_add_co_u32_e32 v32, vcc, s6, v18
	s_mov_b32 s6, 0x27000
	s_nop 0
	v_addc_co_u32_e32 v33, vcc, 0, v19, vcc
	v_add_co_u32_e32 v34, vcc, s6, v18
	s_mov_b32 s6, 0x2a000
	s_nop 0
	v_addc_co_u32_e32 v35, vcc, 0, v19, vcc
	v_add_co_u32_e32 v36, vcc, s6, v18
	s_mov_b32 s6, 0x2d000
	s_nop 0
	v_addc_co_u32_e32 v37, vcc, 0, v19, vcc
	v_add_co_u32_e32 v38, vcc, s6, v18
	s_mov_b32 s6, 0x30000
	s_nop 0
	v_addc_co_u32_e32 v39, vcc, 0, v19, vcc
	global_load_dword v47, v[10:11], off
	global_load_dword v48, v[12:13], off
	global_load_dword v49, v[28:29], off
	global_load_dword v50, v[30:31], off
	global_load_dword v51, v[32:33], off
	global_load_dword v52, v[34:35], off
	global_load_dword v53, v[36:37], off
	global_load_dword v54, v[38:39], off
	v_add_co_u32_e32 v10, vcc, s6, v18
	s_mov_b32 s6, 0x33000
	s_nop 0
	v_addc_co_u32_e32 v11, vcc, 0, v19, vcc
	v_add_co_u32_e32 v12, vcc, s6, v18
	s_mov_b32 s6, 0x36000
	s_nop 0
	v_addc_co_u32_e32 v13, vcc, 0, v19, vcc
	v_add_co_u32_e32 v28, vcc, s6, v18
	s_mov_b32 s6, 0x39000
	s_nop 0
	v_addc_co_u32_e32 v29, vcc, 0, v19, vcc
	v_add_co_u32_e32 v30, vcc, s6, v18
	s_waitcnt vmcnt(15) lgkmcnt(1)
	v_fma_f32 v70, v27, v6, 0
	v_addc_co_u32_e32 v31, vcc, 0, v19, vcc
	v_add_co_u32_e32 v32, vcc, s9, v18
	s_waitcnt vmcnt(14)
	v_fmac_f32_e32 v70, v40, v7
	v_addc_co_u32_e32 v33, vcc, 0, v19, vcc
	v_add_co_u32_e32 v34, vcc, s10, v18
	s_waitcnt vmcnt(13)
	v_fmac_f32_e32 v70, v41, v8
	v_addc_co_u32_e32 v35, vcc, 0, v19, vcc
	v_add_co_u32_e32 v36, vcc, s11, v18
	s_waitcnt vmcnt(12)
; __global__ void __launch_bounds__(NTHR, 2) hybrid_fwd(Args a) {
;     ...
;             const float* W = a.ada_w + (size_t)l * D * 3072 + (size_t)(kc * 64) * 3072 + n;
;             float a0 = 0.f, a1 = 0.f;
; #pragma unroll
;             for (int k = 0; k < 64; ++k) { const float wv = W[(size_t)k * 3072]; a0 += sc_l[kc * 64 + k] * wv; a1 += sc_l[D + kc * 64 + k] * wv; }
;             red[(kc * 2 + 0) * 32 + (lane & 31)] = a0; red[(kc * 2 + 1) * 32 + (lane & 31)] = a1;
	v_fmac_f32_e32 v70, v42, v9
	v_addc_co_u32_e32 v37, vcc, 0, v19, vcc
	v_add_co_u32_e32 v38, vcc, s12, v18
	s_waitcnt vmcnt(11) lgkmcnt(0)
	v_fmac_f32_e32 v70, v43, v2
	v_addc_co_u32_e32 v39, vcc, 0, v19, vcc
	global_load_dword v55, v[10:11], off
	global_load_dword v56, v[12:13], off
	global_load_dword v57, v[28:29], off
	global_load_dword v58, v[30:31], off
	global_load_dword v59, v[32:33], off
	global_load_dword v60, v[34:35], off
	global_load_dword v61, v[36:37], off
	global_load_dword v62, v[38:39], off
	v_add_co_u32_e32 v10, vcc, s13, v18
	s_waitcnt vmcnt(18)
	v_fmac_f32_e32 v70, v44, v3
	v_addc_co_u32_e32 v11, vcc, 0, v19, vcc
	v_add_co_u32_e32 v12, vcc, s14, v18
	s_waitcnt vmcnt(17)
	v_fmac_f32_e32 v70, v45, v4
	v_addc_co_u32_e32 v13, vcc, 0, v19, vcc
	global_load_dword v63, v[10:11], off
	global_load_dword v64, v[12:13], off
	v_add_co_u32_e32 v10, vcc, s15, v18
	s_waitcnt vmcnt(18)
	v_fmac_f32_e32 v70, v46, v5
	v_addc_co_u32_e32 v11, vcc, 0, v19, vcc
	v_add_co_u32_e32 v12, vcc, s18, v18
	s_nop 1
	v_addc_co_u32_e32 v13, vcc, 0, v19, vcc
	v_add_co_u32_e32 v28, vcc, s19, v18
	s_nop 1
	v_addc_co_u32_e32 v29, vcc, 0, v19, vcc
	v_add_co_u32_e32 v30, vcc, s22, v18
	s_nop 1
	v_addc_co_u32_e32 v31, vcc, 0, v19, vcc
	global_load_dword v65, v[10:11], off
	global_load_dword v66, v[12:13], off
	global_load_dword v67, v[28:29], off
	global_load_dword v68, v[30:31], off
	v_add_co_u32_e32 v10, vcc, s23, v18
	s_nop 1
	v_addc_co_u32_e32 v11, vcc, 0, v19, vcc
	global_load_dword v69, v[10:11], off
	ds_read_b128 v[10:13], v20 offset:4096
	ds_read_b128 v[28:31], v20 offset:32
	ds_read_b128 v[32:35], v20 offset:48
	ds_read_b128 v[36:39], v20 offset:4112
	ds_read_b128 v[6:9], v20 offset:4128
	s_waitcnt lgkmcnt(4)
	v_fma_f32 v27, v27, v10, 0
	v_fmac_f32_e32 v27, v40, v11
	v_fmac_f32_e32 v27, v41, v12
	v_fmac_f32_e32 v27, v42, v13
	s_waitcnt lgkmcnt(1)
	v_fmac_f32_e32 v27, v43, v36
	v_fmac_f32_e32 v27, v44, v37
	v_fmac_f32_e32 v27, v45, v38
	v_fmac_f32_e32 v27, v46, v39
	ds_read_b128 v[2:5], v20 offset:4144
	ds_read_b128 v[10:13], v20 offset:4160
	s_waitcnt vmcnt(22)
	v_fmac_f32_e32 v70, v47, v28
	s_waitcnt lgkmcnt(2)
	v_fmac_f32_e32 v27, v47, v6
	s_waitcnt vmcnt(21)
	v_fmac_f32_e32 v70, v48, v29
	v_fmac_f32_e32 v27, v48, v7
	s_waitcnt vmcnt(20)
	v_fmac_f32_e32 v70, v49, v30
	v_fmac_f32_e32 v27, v49, v8
	s_waitcnt vmcnt(19)
	v_fmac_f32_e32 v70, v50, v31
	v_fmac_f32_e32 v27, v50, v9
	ds_read_b128 v[6:9], v20 offset:64
	s_waitcnt vmcnt(18)
	v_fmac_f32_e32 v70, v51, v32
	s_waitcnt lgkmcnt(2)
	v_fmac_f32_e32 v27, v51, v2
	s_waitcnt vmcnt(17)
	v_fmac_f32_e32 v70, v52, v33
	v_fmac_f32_e32 v27, v52, v3
	s_waitcnt vmcnt(16)
	v_fmac_f32_e32 v70, v53, v34
	v_fmac_f32_e32 v27, v53, v4
	s_waitcnt vmcnt(15)
	v_fmac_f32_e32 v70, v54, v35
	v_fmac_f32_e32 v27, v54, v5
	ds_read_b128 v[2:5], v20 offset:80
	ds_read_b128 v[28:31], v20 offset:4176
	s_waitcnt vmcnt(14) lgkmcnt(2)
	v_fmac_f32_e32 v70, v55, v6
	v_fmac_f32_e32 v27, v55, v10
	s_waitcnt vmcnt(13)
	v_fmac_f32_e32 v70, v56, v7
	v_fmac_f32_e32 v27, v56, v11
	s_waitcnt vmcnt(12)
	v_fmac_f32_e32 v70, v57, v8
	v_fmac_f32_e32 v27, v57, v12
	s_waitcnt vmcnt(11)
	v_fmac_f32_e32 v70, v58, v9
	v_fmac_f32_e32 v27, v58, v13
	s_waitcnt vmcnt(10) lgkmcnt(1)
	v_fmac_f32_e32 v70, v59, v2
	s_waitcnt lgkmcnt(0)
	v_fmac_f32_e32 v27, v59, v28
	s_waitcnt vmcnt(9)
	v_fmac_f32_e32 v70, v60, v3
	v_fmac_f32_e32 v27, v60, v29
	s_waitcnt vmcnt(8)
	v_fmac_f32_e32 v70, v61, v4
	v_fmac_f32_e32 v27, v61, v30
	s_waitcnt vmcnt(7)
	v_fmac_f32_e32 v70, v62, v5
	v_fmac_f32_e32 v27, v62, v31
	ds_read_b128 v[10:13], v20 offset:4192
	ds_read_b128 v[28:31], v20 offset:96
	ds_read_b128 v[2:5], v20 offset:112
	v_add_co_u32_e32 v6, vcc, s35, v18
	s_waitcnt vmcnt(6) lgkmcnt(2)
	v_fmac_f32_e32 v27, v63, v10
	v_addc_co_u32_e32 v7, vcc, 0, v19, vcc
	s_waitcnt lgkmcnt(1)
	v_fmac_f32_e32 v70, v63, v28
	global_load_dword v40, v[6:7], off
	ds_read_b128 v[6:9], v20 offset:4208
	s_waitcnt vmcnt(6)
	v_fmac_f32_e32 v70, v64, v29
	v_fmac_f32_e32 v27, v64, v11
	s_waitcnt vmcnt(5)
	v_fmac_f32_e32 v70, v65, v30
	s_waitcnt vmcnt(4)
	v_fmac_f32_e32 v70, v66, v31
	v_fmac_f32_e32 v27, v65, v12
	s_waitcnt vmcnt(3) lgkmcnt(1)
	v_fmac_f32_e32 v70, v67, v2
	v_add_co_u32_e32 v2, vcc, s56, v18
	v_fmac_f32_e32 v27, v66, v13
	s_waitcnt vmcnt(2)
	v_fmac_f32_e32 v70, v68, v3
	v_addc_co_u32_e32 v3, vcc, 0, v19, vcc
	ds_read_b128 v[10:13], v20 offset:128
	s_waitcnt lgkmcnt(1)
	v_fmac_f32_e32 v27, v67, v6
	v_add_co_u32_e32 v6, vcc, s57, v18
	v_fmac_f32_e32 v27, v68, v7
	s_nop 0
	v_addc_co_u32_e32 v7, vcc, 0, v19, vcc
	v_add_co_u32_e32 v28, vcc, s64, v18
	s_waitcnt vmcnt(1)
	v_fmac_f32_e32 v70, v69, v4
	v_addc_co_u32_e32 v29, vcc, 0, v19, vcc
	v_add_co_u32_e32 v30, vcc, s65, v18
	v_fmac_f32_e32 v27, v69, v8
	s_nop 0
	v_addc_co_u32_e32 v31, vcc, 0, v19, vcc
	v_add_co_u32_e32 v32, vcc, s67, v18
	s_waitcnt vmcnt(0)
	v_fmac_f32_e32 v70, v40, v5
	v_addc_co_u32_e32 v33, vcc, 0, v19, vcc
	v_add_co_u32_e32 v34, vcc, s68, v18
	v_fmac_f32_e32 v27, v40, v9
	s_nop 0
	v_addc_co_u32_e32 v35, vcc, 0, v19, vcc
	v_add_co_u32_e32 v36, vcc, s69, v18
	s_nop 1
	v_addc_co_u32_e32 v37, vcc, 0, v19, vcc
	v_add_co_u32_e32 v38, vcc, s70, v18
	s_nop 1
	v_addc_co_u32_e32 v39, vcc, 0, v19, vcc
	global_load_dword v41, v[2:3], off
	global_load_dword v42, v[6:7], off
	global_load_dword v43, v[28:29], off
	global_load_dword v44, v[30:31], off
	global_load_dword v45, v[32:33], off
	global_load_dword v46, v[34:35], off
	global_load_dword v47, v[36:37], off
	global_load_dword v48, v[38:39], off
	v_add_co_u32_e32 v2, vcc, s71, v18
	s_waitcnt vmcnt(7) lgkmcnt(0)
	v_fmac_f32_e32 v70, v41, v10
	v_addc_co_u32_e32 v3, vcc, 0, v19, vcc
	v_add_co_u32_e32 v6, vcc, s72, v18
	s_waitcnt vmcnt(6)
; __global__ void __launch_bounds__(NTHR, 2) hybrid_fwd(Args a) {
;     ...
;             const float* W = a.ada_w + (size_t)l * D * 3072 + (size_t)(kc * 64) * 3072 + n;
;             float a0 = 0.f, a1 = 0.f;
; #pragma unroll
;             for (int k = 0; k < 64; ++k) { const float wv = W[(size_t)k * 3072]; a0 += sc_l[kc * 64 + k] * wv; a1 += sc_l[D + kc * 64 + k] * wv; }
;             red[(kc * 2 + 0) * 32 + (lane & 31)] = a0; red[(kc * 2 + 1) * 32 + (lane & 31)] = a1;
;             __syncthreads();
	v_fmac_f32_e32 v70, v42, v11
	v_addc_co_u32_e32 v7, vcc, 0, v19, vcc
	v_add_co_u32_e32 v28, vcc, s73, v18
	s_waitcnt vmcnt(5)
	v_fmac_f32_e32 v70, v43, v12
	v_addc_co_u32_e32 v29, vcc, 0, v19, vcc
	v_add_co_u32_e32 v30, vcc, s74, v18
	s_waitcnt vmcnt(4)
	v_fmac_f32_e32 v70, v44, v13
	v_addc_co_u32_e32 v31, vcc, 0, v19, vcc
	v_add_co_u32_e32 v32, vcc, s75, v18
	s_nop 1
	v_addc_co_u32_e32 v33, vcc, 0, v19, vcc
	v_add_co_u32_e32 v34, vcc, s76, v18
	s_nop 1
	v_addc_co_u32_e32 v35, vcc, 0, v19, vcc
	v_add_co_u32_e32 v36, vcc, s77, v18
	s_nop 1
	v_addc_co_u32_e32 v37, vcc, 0, v19, vcc
	v_add_co_u32_e32 v38, vcc, s80, v18
	s_nop 1
	v_addc_co_u32_e32 v39, vcc, 0, v19, vcc
	global_load_dword v49, v[2:3], off
	global_load_dword v50, v[6:7], off
	global_load_dword v51, v[28:29], off
	global_load_dword v52, v[30:31], off
	global_load_dword v53, v[32:33], off
	global_load_dword v54, v[34:35], off
	global_load_dword v55, v[36:37], off
	global_load_dword v56, v[38:39], off
	v_add_co_u32_e32 v2, vcc, s81, v18
	s_nop 1
	v_addc_co_u32_e32 v3, vcc, 0, v19, vcc
	v_add_co_u32_e32 v6, vcc, s82, v18
	s_nop 1
	v_addc_co_u32_e32 v7, vcc, 0, v19, vcc
	v_add_co_u32_e32 v28, vcc, s83, v18
	s_nop 1
	v_addc_co_u32_e32 v29, vcc, 0, v19, vcc
	v_add_co_u32_e32 v30, vcc, s85, v18
	s_nop 1
	v_addc_co_u32_e32 v31, vcc, 0, v19, vcc
	v_add_co_u32_e32 v32, vcc, s86, v18
	s_nop 1
	v_addc_co_u32_e32 v33, vcc, 0, v19, vcc
	v_add_co_u32_e32 v34, vcc, s87, v18
	s_nop 1
	v_addc_co_u32_e32 v35, vcc, 0, v19, vcc
	v_add_co_u32_e32 v36, vcc, s88, v18
	s_nop 1
	v_addc_co_u32_e32 v37, vcc, 0, v19, vcc
	v_add_co_u32_e32 v38, vcc, s89, v18
	s_nop 1
	v_addc_co_u32_e32 v39, vcc, 0, v19, vcc
	global_load_dword v57, v[2:3], off
	global_load_dword v58, v[6:7], off
	global_load_dword v59, v[28:29], off
	global_load_dword v60, v[30:31], off
	global_load_dword v61, v[32:33], off
	s_nop 0
	global_load_dword v34, v[34:35], off
	s_nop 0
	global_load_dword v35, v[36:37], off
	s_nop 0
	global_load_dword v36, v[38:39], off
	v_add_co_u32_e32 v2, vcc, s90, v18
	s_nop 1
	v_addc_co_u32_e32 v3, vcc, 0, v19, vcc
	v_add_co_u32_e32 v6, vcc, s91, v18
	s_nop 1
	v_addc_co_u32_e32 v7, vcc, 0, v19, vcc
	global_load_dword v37, v[2:3], off
	global_load_dword v38, v[6:7], off
	v_add_co_u32_e32 v2, vcc, s92, v18
	s_nop 1
	v_addc_co_u32_e32 v3, vcc, 0, v19, vcc
	v_add_co_u32_e32 v6, vcc, s93, v18
	s_nop 1
	v_addc_co_u32_e32 v7, vcc, 0, v19, vcc
	v_add_co_u32_e32 v28, vcc, s94, v18
	s_nop 1
	v_addc_co_u32_e32 v29, vcc, 0, v19, vcc
	v_add_co_u32_e32 v30, vcc, s95, v18
	s_nop 1
	v_addc_co_u32_e32 v31, vcc, 0, v19, vcc
	v_add_co_u32_e32 v32, vcc, s96, v18
	s_nop 1
	v_addc_co_u32_e32 v33, vcc, 0, v19, vcc
	global_load_dword v39, v[2:3], off
	global_load_dword v62, v[6:7], off
	global_load_dword v63, v[28:29], off
	global_load_dword v64, v[30:31], off
	s_nop 0
	global_load_dword v32, v[32:33], off
	v_add_co_u32_e32 v2, vcc, 0xbd000, v18
	ds_read_b128 v[6:9], v20 offset:144
	s_nop 0
	v_addc_co_u32_e32 v3, vcc, 0, v19, vcc
	global_load_dword v18, v[2:3], off
	ds_read_b128 v[2:5], v20 offset:4224
	ds_read_b128 v[10:13], v20 offset:176
	ds_read_b128 v[28:31], v20 offset:4240
	s_waitcnt lgkmcnt(2)
	v_fmac_f32_e32 v27, v41, v2
	v_fmac_f32_e32 v27, v42, v3
	v_fmac_f32_e32 v27, v43, v4
	v_fmac_f32_e32 v27, v44, v5
	ds_read_b128 v[2:5], v20 offset:160
	s_waitcnt vmcnt(27)
	v_fmac_f32_e32 v70, v45, v6
	s_waitcnt vmcnt(26)
	v_fmac_f32_e32 v70, v46, v7
	s_waitcnt vmcnt(25)
	v_fmac_f32_e32 v70, v47, v8
	s_waitcnt vmcnt(24)
	v_fmac_f32_e32 v70, v48, v9
	s_waitcnt vmcnt(23) lgkmcnt(0)
	v_fmac_f32_e32 v70, v49, v2
	s_waitcnt vmcnt(22)
	v_fmac_f32_e32 v70, v50, v3
	s_waitcnt vmcnt(21)
	v_fmac_f32_e32 v70, v51, v4
	s_waitcnt vmcnt(20)
	v_fmac_f32_e32 v70, v52, v5
	ds_read_b128 v[2:5], v20 offset:192
	s_waitcnt vmcnt(19)
	v_fmac_f32_e32 v70, v53, v10
	s_waitcnt vmcnt(18)
	v_fmac_f32_e32 v70, v54, v11
	s_waitcnt vmcnt(17)
	v_fmac_f32_e32 v70, v55, v12
	s_waitcnt vmcnt(16)
	v_fmac_f32_e32 v70, v56, v13
	ds_read_b128 v[10:13], v20 offset:208
	ds_read_b128 v[6:9], v20 offset:4256
	s_waitcnt vmcnt(15) lgkmcnt(2)
	v_fmac_f32_e32 v70, v57, v2
	s_waitcnt vmcnt(14)
	v_fmac_f32_e32 v70, v58, v3
	s_waitcnt vmcnt(13)
	v_fmac_f32_e32 v70, v59, v4
	s_waitcnt vmcnt(12)
	v_fmac_f32_e32 v70, v60, v5
	ds_read_b128 v[2:5], v20 offset:224
	s_waitcnt vmcnt(11) lgkmcnt(2)
	v_fmac_f32_e32 v70, v61, v10
	s_waitcnt vmcnt(10)
	v_fmac_f32_e32 v70, v34, v11
	s_waitcnt vmcnt(9)
	v_fmac_f32_e32 v70, v35, v12
	s_waitcnt vmcnt(8)
	v_fmac_f32_e32 v70, v36, v13
	ds_read_b128 v[10:13], v20 offset:240
	v_fmac_f32_e32 v27, v45, v28
	v_fmac_f32_e32 v27, v46, v29
	v_fmac_f32_e32 v27, v47, v30
	v_fmac_f32_e32 v27, v48, v31
	ds_read_b128 v[28:31], v20 offset:4272
	s_waitcnt lgkmcnt(3)
	v_fmac_f32_e32 v27, v49, v6
	v_fmac_f32_e32 v27, v50, v7
	v_fmac_f32_e32 v27, v51, v8
	v_fmac_f32_e32 v27, v52, v9
	ds_read_b128 v[6:9], v20 offset:4288
	s_waitcnt lgkmcnt(1)
	v_fmac_f32_e32 v27, v53, v28
	v_fmac_f32_e32 v27, v54, v29
	v_fmac_f32_e32 v27, v55, v30
	v_fmac_f32_e32 v27, v56, v31
	ds_read_b128 v[28:31], v20 offset:4304
	s_waitcnt lgkmcnt(1)
	v_fmac_f32_e32 v27, v57, v6
	v_fmac_f32_e32 v27, v58, v7
	v_fmac_f32_e32 v27, v59, v8
	v_fmac_f32_e32 v27, v60, v9
	ds_read_b128 v[6:9], v20 offset:4320
	s_waitcnt lgkmcnt(1)
	v_fmac_f32_e32 v27, v61, v28
	v_fmac_f32_e32 v27, v34, v29
	v_fmac_f32_e32 v27, v35, v30
	v_fmac_f32_e32 v27, v36, v31
	ds_read_b128 v[28:31], v20 offset:4336
	s_waitcnt vmcnt(7)
	v_fmac_f32_e32 v70, v37, v2
	s_waitcnt lgkmcnt(1)
	v_fmac_f32_e32 v27, v37, v6
	s_waitcnt vmcnt(6)
	v_fmac_f32_e32 v70, v38, v3
	v_fmac_f32_e32 v27, v38, v7
	s_waitcnt vmcnt(5)
	v_fmac_f32_e32 v70, v39, v4
	v_fmac_f32_e32 v27, v39, v8
	s_waitcnt vmcnt(4)
	v_fmac_f32_e32 v70, v62, v5
	v_fmac_f32_e32 v27, v62, v9
	s_waitcnt vmcnt(3)
	v_fmac_f32_e32 v70, v63, v10
	s_waitcnt lgkmcnt(0)
	v_fmac_f32_e32 v27, v63, v28
	s_waitcnt vmcnt(2)
	v_fmac_f32_e32 v70, v64, v11
	v_fmac_f32_e32 v27, v64, v29
	s_waitcnt vmcnt(1)
	v_fmac_f32_e32 v70, v32, v12
	v_fmac_f32_e32 v27, v32, v30
	s_waitcnt vmcnt(0)
	v_fmac_f32_e32 v70, v18, v13
	v_fmac_f32_e32 v27, v18, v31
	ds_write2_b32 v26, v70, v27 offset1:32
	s_waitcnt lgkmcnt(0)
	s_barrier
; __global__ void __launch_bounds__(NTHR, 2) hybrid_fwd(Args a) {
;     ...
;             if (tid < 64) { const int b = tid >> 5, nn = tid & 31; float s = 0.f;
; #pragma unroll
;                 for (int k = 0; k < 16; ++k) s += red[(k * 2 + b) * 32 + nn];
;                 MOD[(l * 2 + b) * 3072 + n0 + nn] = s + a.ada_b[l * 3072 + n0 + nn]; }
	s_and_saveexec_b64 s[6:7], s[0:1]
	s_cbranch_execz .LBB0_11
	s_mul_i32 s59, s99, 0xc00
	s_add_i32 s59, s59, s58
	v_or_b32_e32 v2, s59, v1
	v_ashrrev_i32_e32 v3, 31, v2
	v_lshl_add_u64 v[2:3], v[2:3], 2, s[24:25]
	global_load_dword v27, v[2:3], off
	ds_read2st64_b32 v[2:3], v22 offset0:32 offset1:33
	ds_read2st64_b32 v[4:5], v22 offset0:34 offset1:35
	ds_read2st64_b32 v[6:7], v22 offset0:36 offset1:37
	ds_read2st64_b32 v[8:9], v22 offset0:38 offset1:39
	ds_read2st64_b32 v[10:11], v22 offset0:40 offset1:41
	ds_read2st64_b32 v[12:13], v22 offset0:42 offset1:43
	ds_read2st64_b32 v[18:19], v22 offset0:44 offset1:45
	ds_read2st64_b32 v[28:29], v22 offset0:46 offset1:47
	s_waitcnt lgkmcnt(7)
	v_add_f32_e32 v2, 0, v2
	v_add_f32_e32 v2, v2, v3
	s_waitcnt lgkmcnt(6)
	v_add_f32_e32 v2, v2, v4
	v_add_f32_e32 v2, v2, v5
	s_waitcnt lgkmcnt(5)
	v_add_f32_e32 v2, v2, v6
	v_add_f32_e32 v2, v2, v7
	s_waitcnt lgkmcnt(4)
	v_add_f32_e32 v2, v2, v8
	v_add_f32_e32 v2, v2, v9
	s_waitcnt lgkmcnt(3)
	v_add_f32_e32 v2, v2, v10
	v_add_f32_e32 v2, v2, v11
	s_waitcnt lgkmcnt(2)
	v_add_f32_e32 v2, v2, v12
	v_lshl_or_b32 v30, s99, 1, v21
	v_add_f32_e32 v2, v2, v13
	v_mul_lo_u32 v30, v30, s97
	s_waitcnt lgkmcnt(1)
	v_add_f32_e32 v2, v2, v18
	v_add_u32_e32 v30, s58, v30
	v_add_f32_e32 v2, v2, v19
	v_or_b32_e32 v30, v30, v1
	s_waitcnt lgkmcnt(0)
	v_add_f32_e32 v2, v2, v28
	v_ashrrev_i32_e32 v31, 31, v30
	v_add_f32_e32 v2, v2, v29
	s_waitcnt vmcnt(0)
	v_add_f32_e32 v4, v2, v27
	v_lshl_add_u64 v[2:3], v[30:31], 2, s[60:61]
	global_store_dword v[2:3], v4, off
	s_branch .LBB0_11
